# attention: younger half (waves 4-7) staggered by s_sleep 20 after the K/V staging barrier
# speedup vs baseline: 1.0075x; 1.0075x over previous
.LBB0_410:
	s_or_b64 exec, exec, s[0:1]
	s_bfe_u32 s0, s22, 0x20006
	s_lshl_b32 s1, s23, 2
	s_or_b32 s23, s0, s1
	s_add_i32 s0, s23, 1
	v_and_b32_e32 v55, 15, v1
	v_bfe_u32 v0, v1, 4, 2
	v_cvt_f32_ubyte0_e32 v1, s0
	v_mul_f32_e32 v2, -0.5, v1
	s_mov_b32 s0, 0xc2fc0000
	v_cmp_gt_f32_e32 vcc, s0, v2
	v_mov_b32_e32 v2, 0x42800000
	s_and_b64 s[0:1], vcc, exec
	v_cndmask_b32_e32 v2, 0, v2, vcc
	v_fmac_f32_e32 v2, -0.5, v1
	v_exp_f32_e32 v1, v2
	s_cselect_b32 s0, 0xffffffc0, 0
	s_waitcnt lgkmcnt(0)
	s_barrier
	s_cmpk_lt_u32 s22, 0x100
	s_cbranch_scc1 .Lattn_nostag
	s_sleep 20
.Lattn_nostag:
	v_ldexp_f32 v49, v1, s0
	s_lshl_b32 s0, s23, 2
	v_mov_b32_e32 v1, s0
	v_readlane_b32 s0, v252, 56
	v_readlane_b32 s6, v252, 62
	v_readlane_b32 s7, v252, 63
	s_ashr_i32 s31, s22, 8
	s_cmp_lg_u32 s20, 0
	s_cselect_b64 s[82:83], -1, 0
	s_lshl_b32 s0, s23, 6
	s_nop 0
	global_load_dword v57, v1, s[6:7]
	s_cmp_lt_u32 s21, 2
	s_cselect_b64 s[74:75], -1, 0
	s_lshl_b32 s37, s31, 4
	v_lshlrev_b32_e32 v50, 3, v0
	v_lshl_add_u32 v52, v0, 4, 0
	v_lshlrev_b32_e32 v54, 2, v0
	v_and_or_b32 v0, s37, 16, v55
	v_or_b32_e32 v0, 0x80, v0
	v_readlane_b32 s2, v252, 58
	v_readlane_b32 s3, v252, 59
	v_sub_u32_e32 v1, v0, v54
	v_cvt_f32_ubyte0_e32 v0, v1
	s_mov_b32 s2, 2.0
	v_mul_f32_e32 v0, v49, v0
	v_mov_b32_e32 v2, v49
	s_mov_b32 s3, 0x40400000
	v_pk_fma_f32 v[60:61], v[2:3], s[2:3], v[0:1] op_sel_hi:[0,1,0] neg_lo:[0,0,1] neg_hi:[0,0,1]
	s_mov_b32 s2, 0x41800000
	s_mov_b32 s3, 0x41880000
	v_pk_fma_f32 v[62:63], v[2:3], s[2:3], v[0:1] op_sel_hi:[0,1,0] neg_lo:[0,0,1] neg_hi:[0,0,1]
	s_mov_b32 s2, 0x41900000
	s_mov_b32 s3, 0x41980000
	v_pk_fma_f32 v[64:65], v[2:3], s[2:3], v[0:1] op_sel_hi:[0,1,0] neg_lo:[0,0,1] neg_hi:[0,0,1]
	s_mov_b32 s2, 0x42000000
	s_mov_b32 s3, 0x42040000
	v_pk_fma_f32 v[66:67], v[2:3], s[2:3], v[0:1] op_sel_hi:[0,1,0] neg_lo:[0,0,1] neg_hi:[0,0,1]
	s_mov_b32 s2, 0x42080000
	s_mov_b32 s3, 0x420c0000
	v_pk_fma_f32 v[68:69], v[2:3], s[2:3], v[0:1] op_sel_hi:[0,1,0] neg_lo:[0,0,1] neg_hi:[0,0,1]
	s_mov_b32 s2, 0x42400000
	s_mov_b32 s3, 0x42440000
	v_pk_fma_f32 v[70:71], v[2:3], s[2:3], v[0:1] op_sel_hi:[0,1,0] neg_lo:[0,0,1] neg_hi:[0,0,1]
	s_mov_b32 s2, 0x42480000
	s_mov_b32 s3, 0x424c0000
	v_pk_fma_f32 v[72:73], v[2:3], s[2:3], v[0:1] op_sel_hi:[0,1,0] neg_lo:[0,0,1] neg_hi:[0,0,1]
	s_mov_b32 s2, 0x42800000
	s_mov_b32 s3, 0x42820000
	v_pk_fma_f32 v[74:75], v[2:3], s[2:3], v[0:1] op_sel_hi:[0,1,0] neg_lo:[0,0,1] neg_hi:[0,0,1]
	s_mov_b32 s2, 0x42840000
	s_mov_b32 s3, 0x42860000
	v_pk_fma_f32 v[76:77], v[2:3], s[2:3], v[0:1] op_sel_hi:[0,1,0] neg_lo:[0,0,1] neg_hi:[0,0,1]
	s_mov_b32 s2, 0x42a00000
	s_mov_b32 s3, 0x42a20000
	v_pk_fma_f32 v[78:79], v[2:3], s[2:3], v[0:1] op_sel_hi:[0,1,0] neg_lo:[0,0,1] neg_hi:[0,0,1]
	s_mov_b32 s2, 0x42a40000
	s_mov_b32 s3, 0x42a60000
	v_pk_fma_f32 v[80:81], v[2:3], s[2:3], v[0:1] op_sel_hi:[0,1,0] neg_lo:[0,0,1] neg_hi:[0,0,1]
	s_mov_b32 s2, 0x42c00000
	s_mov_b32 s3, 0x42c20000
	v_pk_fma_f32 v[82:83], v[2:3], s[2:3], v[0:1] op_sel_hi:[0,1,0] neg_lo:[0,0,1] neg_hi:[0,0,1]
	s_mov_b32 s2, 0x42c40000
	s_mov_b32 s3, 0x42c60000
	v_pk_fma_f32 v[84:85], v[2:3], s[2:3], v[0:1] op_sel_hi:[0,1,0] neg_lo:[0,0,1] neg_hi:[0,0,1]
	s_mov_b32 s2, 0x42e00000
	s_mov_b32 s3, 0x42e20000
	v_pk_fma_f32 v[86:87], v[2:3], s[2:3], v[0:1] op_sel_hi:[0,1,0] neg_lo:[0,0,1] neg_hi:[0,0,1]
	s_mov_b32 s2, 0x42e40000
	v_add_u32_e32 v5, -2, v1
	s_mov_b32 s3, 0x42e60000
	v_cmp_gt_u32_e64 s[44:45], s69, v5
	v_add_u32_e32 v5, -16, v1
	v_pk_fma_f32 v[88:89], v[2:3], s[2:3], v[0:1] op_sel_hi:[0,1,0] neg_lo:[0,0,1] neg_hi:[0,0,1]
	s_mov_b32 s2, 0x43010000
	v_readlane_b32 s1, v252, 57
	v_add_u32_e32 v6, -3, v1
	v_cmp_gt_u32_e64 s[48:49], s69, v5
	v_subrev_u32_e32 v5, 18, v1
	s_mov_b32 s3, 0x43020000
	s_movk_i32 s1, 0x81
	v_cmp_gt_u32_e64 s[42:43], s69, v6
	v_subrev_u32_e32 v6, 17, v1
	v_cmp_gt_u32_e64 s[52:53], s69, v5
	v_add_u32_e32 v5, 0xffffff7f, v1
	v_pk_fma_f32 v[90:91], v[2:3], s[2:3], v[0:1] op_sel_hi:[0,1,0] neg_lo:[0,0,1] neg_hi:[0,0,1]
	s_mov_b32 s2, 0x43100000
	v_cmp_gt_u32_e64 s[40:41], s1, v1
	v_cmp_gt_u32_e64 s[46:47], s69, v6
	v_subrev_u32_e32 v6, 19, v1
	s_mov_b32 s1, 0x43000000
	v_cmp_gt_u32_e64 s[56:57], s69, v5
	v_add_u32_e32 v5, 0xffffff7d, v1
	s_mov_b32 s3, 0x43110000
	v_mul_f32_e32 v48, 0, v49
	v_cmp_gt_u32_e64 s[50:51], s69, v6
	v_fma_f32 v125, v49, s1, -v0
	v_add_u32_e32 v6, 0xffffff7e, v1
	v_cmp_gt_u32_e64 s[58:59], s69, v5
	s_mov_b32 s1, 0x43030000
	v_add_u32_e32 v5, 0xffffff70, v1
	v_pk_fma_f32 v[92:93], v[2:3], s[2:3], v[0:1] op_sel_hi:[0,1,0] neg_lo:[0,0,1] neg_hi:[0,0,1]
	s_mov_b32 s2, 0x43120000
	v_cmp_gt_u32_e64 s[38:39], s69, v1
	v_pk_add_f32 v[58:59], v[48:49], v[0:1] op_sel_hi:[1,0] neg_lo:[0,1] neg_hi:[0,1]
	v_cmp_gt_u32_e64 s[54:55], s69, v6
	v_fma_f32 v126, v49, s1, -v0
	v_add_u32_e32 v6, 0xffffff6f, v1
	v_cmp_gt_u32_e64 s[62:63], s69, v5
	v_add_u32_e32 v5, 0xffffff6e, v1
	v_add_u32_e32 v1, 0xffffff6d, v1
	s_mov_b32 s3, 0x43130000
	v_readlane_b32 s1, v254, 37
	v_pk_fma_f32 v[94:95], v[2:3], s[2:3], v[0:1] op_sel_hi:[0,1,0] neg_lo:[0,0,1] neg_hi:[0,0,1]
	s_sub_i32 s36, 0x8f, s70
	v_mov_b32_e32 v0, s1
	s_movk_i32 s1, 0x230
	v_mul_u32_u24_e32 v4, 0x90, v55
	v_mad_u32_u24 v0, v55, s1, v0
	v_or_b32_e32 v131, s37, v55
	s_add_i32 s70, s70, s37
	s_mov_b32 s30, 0
	v_sub_u32_e32 v124, v52, v50
	v_or_b32_e32 v51, 3, v54
	v_or_b32_e32 v56, 2, v54
	v_cmp_gt_u32_e64 s[60:61], s69, v6
	v_mul_u32_u24_e32 v127, 0x230, v55
	v_mad_u32_u24 v128, v55, s1, 0
	v_add_u32_e32 v129, 0x6900, v0
	v_xor_b32_e32 v130, 0xffffffed, v54
	v_xor_b32_e32 v132, 0xffffffee, v54
	v_xor_b32_e32 v133, 0xffffffef, v54
	v_sub_u32_e32 v134, -16, v54
	v_xor_b32_e32 v135, -3, v54
	v_xor_b32_e32 v136, -2, v54
	v_not_b32_e32 v137, v54
	v_sub_u32_e32 v138, 0, v54
	v_xor_b32_e32 v139, 13, v54
	v_xor_b32_e32 v140, 14, v54
	v_xor_b32_e32 v141, 15, v54
	v_sub_u32_e32 v142, 16, v54
	v_xor_b32_e32 v143, 29, v54
	v_xor_b32_e32 v144, 30, v54
	v_xor_b32_e32 v145, 31, v54
	v_sub_u32_e32 v146, 32, v54
	v_xor_b32_e32 v147, 45, v54
	v_xor_b32_e32 v148, 46, v54
	v_xor_b32_e32 v149, 47, v54
	v_sub_u32_e32 v150, 48, v54
	v_xor_b32_e32 v151, 61, v54
	v_xor_b32_e32 v152, 62, v54
	v_xor_b32_e32 v153, 63, v54
	v_sub_u32_e32 v154, 64, v54
	v_xor_b32_e32 v155, 0x4d, v54
	v_xor_b32_e32 v156, 0x4e, v54
	v_xor_b32_e32 v157, 0x4f, v54
	v_sub_u32_e32 v158, 0x50, v54
	v_xor_b32_e32 v159, 0x5d, v54
	v_xor_b32_e32 v160, 0x5e, v54
	v_xor_b32_e32 v161, 0x5f, v54
	v_sub_u32_e32 v162, 0x60, v54
	v_sub_u32_e32 v163, v131, v54
	v_xor_b32_e32 v164, 0x7d, v54
	v_xor_b32_e32 v165, 0x7e, v54
	v_xor_b32_e32 v166, 0x7f, v54
	v_sub_u32_e32 v167, 0x80, v54
	v_add_u32_e32 v168, s70, v55
	v_add_u32_e32 v169, v52, v4
	s_lshl_b32 s72, s0, 1
	v_cmp_gt_u32_e64 s[64:65], s69, v1
	v_cmp_gt_u32_e64 s[66:67], s69, v5
	v_readlane_b32 s4, v252, 60
	v_readlane_b32 s5, v252, 61
	v_readlane_b32 s8, v253, 0
	v_readlane_b32 s9, v253, 1
	v_readlane_b32 s10, v253, 2
	v_readlane_b32 s11, v253, 3
	v_readlane_b32 s12, v253, 4
	v_readlane_b32 s13, v253, 5
	v_readlane_b32 s14, v253, 6
	v_readlane_b32 s15, v253, 7
	v_lshlrev_b32_e32 v222, 1, v50
	v_add_u32_e32 v222, s72, v222
	v_add_u32_e32 v222, 0x4002800, v222
	v_cmp_lt_i32_e64 s[98:99], 15, v168
	s_nop 1
	v_cndmask_b32_e64 v249, v229, v53, s[98:99]
	v_add_u32_e32 v248, v168, v249
	v_mad_u32_u24 v248, v248, s29, v222
	global_load_dwordx4 v[240:243], v248, s[92:93]
	global_load_dwordx4 v[244:247], v248, s[92:93] offset:64
	s_waitcnt vmcnt(0)
	s_branch .LBB0_413
